# hgA_unit: all 32 strided z loads of a thread issued up front into spare registers (was a sliding window of ~6 interleaved with the gate math), counted vmcnt at first use
# baseline (speedup 1.0000x reference)
.LBB0_310:
	s_and_b32 s13, s12, 31
	s_waitcnt vmcnt(0)
	v_mov_b32_e32 v4, v200
	s_and_b32 s0, s7, 0xfffff000
	s_lshl_b32 s1, s13, 7
	s_or_b32 s0, s0, s1
	v_ashrrev_i32_e32 v0, 2, v4
	s_ashr_i32 s1, s0, 31
	v_ashrrev_i32_e32 v1, 31, v0
	v_lshl_add_u64 v[2:3], s[0:1], 0, v[0:1]
	v_mov_b64_e32 v[12:13], s[22:23]
	s_ashr_i32 s14, s12, 5
	v_mad_u64_u32 v[8:9], s[2:3], v2, s93, v[12:13]
	s_lshl_b32 s2, s14, 6
	s_and_b32 s2, s2, 0xc0
	v_mad_i32_i24 v9, v3, s93, v9
	s_lshl_b32 s96, s2, 1
	v_lshlrev_b32_e32 v1, 5, v4
	v_lshl_add_u64 v[2:3], v[8:9], 0, s[96:97]
	v_and_b32_e32 v128, 0x60, v1
	v_lshl_add_u64 v[2:3], v[2:3], 0, v[128:129]
	s_mov_b64 s[20:21], 0x1b00
	v_lshl_add_u64 v[14:15], v[2:3], 0, s[20:21]
	v_add_co_u32_e32 v2, vcc, s86, v2
	s_movk_i32 s3, 0x90
	s_nop 0
	v_addc_co_u32_e32 v3, vcc, 0, v3, vcc
	global_load_dwordx4 v[8:11], v[2:3], off offset:2816
	global_load_dwordx4 v[18:21], v[14:15], off offset:16
	v_mul_lo_u32 v0, v0, s3
	v_ashrrev_i32_e32 v15, 7, v4
	v_add3_u32 v7, 16, v0, v128
	v_lshlrev_b32_e32 v0, 5, v15
	v_ashrrev_i32_e32 v1, 31, v0
	v_ashrrev_i32_e32 v6, 6, v4
	v_lshl_add_u64 v[0:1], v[0:1], 0, s[0:1]
	v_and_b32_e32 v22, 1, v6
	v_mad_u64_u32 v[2:3], s[0:1], v0, s93, v[12:13]
	v_mad_i32_i24 v3, v1, s93, v3
	v_cmp_eq_u32_e32 vcc, 0, v22
	v_mov_b32_e32 v0, 0x1900
	v_mov_b32_e32 v1, 0x1700
	v_cndmask_b32_e32 v128, v0, v1, vcc
	v_and_b32_e32 v5, 63, v4
	v_lshl_add_u64 v[0:1], v[2:3], 0, v[128:129]
	v_lshl_add_u64 v[0:1], v[0:1], 0, s[96:97]
	v_lshlrev_b32_e32 v128, 1, v5
	v_lshl_add_u64 v[0:1], v[0:1], 0, v[128:129]
	v_add_co_u32_e32 v2, vcc, s86, v0
	s_nop 0
	v_addc_co_u32_e32 v3, vcc, 0, v1, vcc
	s_movk_i32 s0, 0x3000
	v_add_co_u32_e32 v12, vcc, s0, v0
	v_readlane_b32 s0, v255, 33
	s_nop 0
	v_addc_co_u32_e32 v13, vcc, 0, v1, vcc
	s_nop 0
	v_readlane_b32 s1, v255, 34
	s_or_b32 s0, s2, s0
	v_or_b32_e32 v2, s0, v5
	v_readlane_b32 s0, v253, 10
	v_ashrrev_i32_e32 v3, 31, v2
	v_readlane_b32 s1, v253, 11
	v_lshl_add_u32 v75, v22, 10, 16
	s_movk_i32 s2, 0x4400
	v_lshl_add_u64 v[2:3], v[2:3], 2, s[0:1]
	s_movk_i32 s0, 0x5000
	global_load_dword v16, v[2:3], off
	v_add_co_u32_e32 v112, vcc, 0xf80, v0
	s_nop 1
	v_addc_co_u32_e32 v113, vcc, 0, v1, vcc
	global_load_ushort v80, v[112:113], off offset:-3968
	global_load_ushort v81, v[112:113], off offset:3968
	v_add_co_u32_e32 v112, vcc, 0x4d80, v0
	s_nop 1
	v_addc_co_u32_e32 v113, vcc, 0, v1, vcc
	global_load_ushort v82, v[112:113], off offset:-3968
	global_load_ushort v83, v[112:113], off offset:3968
	v_add_co_u32_e32 v112, vcc, 0x8b80, v0
	s_nop 1
	v_addc_co_u32_e32 v113, vcc, 0, v1, vcc
	global_load_ushort v84, v[112:113], off offset:-3968
	global_load_ushort v85, v[112:113], off offset:3968
	v_add_co_u32_e32 v112, vcc, 0xc980, v0
	s_nop 1
	v_addc_co_u32_e32 v113, vcc, 0, v1, vcc
	global_load_ushort v86, v[112:113], off offset:-3968
	global_load_ushort v87, v[112:113], off offset:3968
	v_add_co_u32_e32 v112, vcc, 0x10780, v0
	s_nop 1
	v_addc_co_u32_e32 v113, vcc, 0, v1, vcc
	global_load_ushort v88, v[112:113], off offset:-3968
	global_load_ushort v89, v[112:113], off offset:3968
	v_add_co_u32_e32 v112, vcc, 0x14580, v0
	s_nop 1
	v_addc_co_u32_e32 v113, vcc, 0, v1, vcc
	global_load_ushort v90, v[112:113], off offset:-3968
	global_load_ushort v91, v[112:113], off offset:3968
	v_add_co_u32_e32 v112, vcc, 0x18380, v0
	s_nop 1
	v_addc_co_u32_e32 v113, vcc, 0, v1, vcc
	global_load_ushort v92, v[112:113], off offset:-3968
	global_load_ushort v93, v[112:113], off offset:3968
	v_add_co_u32_e32 v112, vcc, 0x1c180, v0
	s_nop 1
	v_addc_co_u32_e32 v113, vcc, 0, v1, vcc
	global_load_ushort v94, v[112:113], off offset:-3968
	global_load_ushort v95, v[112:113], off offset:3968
	v_add_co_u32_e32 v112, vcc, 0x1ff80, v0
	s_nop 1
	v_addc_co_u32_e32 v113, vcc, 0, v1, vcc
	global_load_ushort v96, v[112:113], off offset:-3968
	global_load_ushort v97, v[112:113], off offset:3968
	v_add_co_u32_e32 v112, vcc, 0x23d80, v0
	s_nop 1
	v_addc_co_u32_e32 v113, vcc, 0, v1, vcc
	global_load_ushort v98, v[112:113], off offset:-3968
	global_load_ushort v99, v[112:113], off offset:3968
	v_add_co_u32_e32 v112, vcc, 0x27b80, v0
	s_nop 1
	v_addc_co_u32_e32 v113, vcc, 0, v1, vcc
	global_load_ushort v100, v[112:113], off offset:-3968
	global_load_ushort v101, v[112:113], off offset:3968
	v_add_co_u32_e32 v112, vcc, 0x2b980, v0
	s_nop 1
	v_addc_co_u32_e32 v113, vcc, 0, v1, vcc
	global_load_ushort v102, v[112:113], off offset:-3968
	global_load_ushort v103, v[112:113], off offset:3968
	v_add_co_u32_e32 v112, vcc, 0x2f780, v0
	s_nop 1
	v_addc_co_u32_e32 v113, vcc, 0, v1, vcc
	global_load_ushort v104, v[112:113], off offset:-3968
	global_load_ushort v105, v[112:113], off offset:3968
	v_add_co_u32_e32 v112, vcc, 0x33580, v0
	s_nop 1
	v_addc_co_u32_e32 v113, vcc, 0, v1, vcc
	global_load_ushort v106, v[112:113], off offset:-3968
	global_load_ushort v107, v[112:113], off offset:3968
	v_add_co_u32_e32 v112, vcc, 0x37380, v0
	s_nop 1
	v_addc_co_u32_e32 v113, vcc, 0, v1, vcc
	global_load_ushort v108, v[112:113], off offset:-3968
	global_load_ushort v109, v[112:113], off offset:3968
	v_add_co_u32_e32 v112, vcc, 0x3b180, v0
	s_nop 1
	v_addc_co_u32_e32 v113, vcc, 0, v1, vcc
	global_load_ushort v110, v[112:113], off offset:-3968
	global_load_ushort v111, v[112:113], off offset:3968
	v_add_co_u32_e32 v2, vcc, s0, v0
	s_movk_i32 s0, 0x7000
	s_nop 0
	v_addc_co_u32_e32 v3, vcc, 0, v1, vcc
	v_add_co_u32_e32 v2, vcc, s0, v0
	s_mov_b32 s0, 0x9000
	s_nop 0
	v_addc_co_u32_e32 v3, vcc, 0, v1, vcc
	v_add_co_u32_e32 v2, vcc, s0, v0
	s_mov_b32 s0, 0xb000
	s_nop 0
	v_addc_co_u32_e32 v3, vcc, 0, v1, vcc
	v_add_co_u32_e64 v2, s[0:1], s0, v0
	v_cmp_eq_u32_e32 vcc, 1, v22
	s_nop 0
	v_addc_co_u32_e64 v3, s[0:1], 0, v1, s[0:1]
	s_waitcnt vmcnt(34)
	ds_write_b128 v7, v[8:11] offset:36864
	s_waitcnt vmcnt(33)
	ds_write_b128 v7, v[18:21] offset:36880
	s_mov_b32 s0, 0xd000
	v_mad_u32_u24 v22, v22, s2, v75
	s_movk_i32 s2, 0x1200
	v_readfirstlane_b32 s15, v6
	v_cmp_gt_i32_e64 s[42:43], 0, v15
	v_cmp_gt_i32_e64 s[40:41], 1, v15
	v_cmp_gt_i32_e64 s[44:45], 2, v15
	s_waitcnt vmcnt(31)
	v_lshlrev_b32_e32 v2, 16, v80
	v_max_f32_e32 v2, v2, v2
	v_med3_f32 v2, v2, s85, v215
	v_mul_f32_e32 v2, 0xbfb8aa3b, v2
	v_exp_f32_e32 v7, v2
	s_waitcnt vmcnt(30)
	v_lshlrev_b32_e32 v3, 16, v81
	v_max_f32_e32 v3, v3, v3
	v_med3_f32 v3, v3, s85, v215
	v_mul_f32_e32 v2, 0xbfb8aa3b, v3
	s_waitcnt vmcnt(29)
	v_lshlrev_b32_e32 v9, 16, v82
	v_exp_f32_e32 v8, v2
	v_max_f32_e32 v2, v9, v9
	v_med3_f32 v2, v2, s85, v215
	v_add_f32_e32 v3, 1.0, v7
	v_mul_f32_e32 v2, 0xbfb8aa3b, v2
	v_rcp_f32_e32 v9, v3
	v_add_f32_e32 v3, 1.0, v8
	v_exp_f32_e32 v14, v2
	v_add_co_u32_e64 v2, s[0:1], s0, v0
	v_rcp_f32_e32 v10, v3
	s_nop 0
	v_addc_co_u32_e64 v3, s[0:1], 0, v1, s[0:1]
	v_add_f32_e32 v2, 1.0, v14
	s_mov_b32 s0, 0xf000
	v_rcp_f32_e32 v17, v2
	v_add_co_u32_e64 v2, s[0:1], s0, v0
	s_waitcnt vmcnt(32)
	v_sub_f32_e32 v11, 1.0, v16
	v_addc_co_u32_e64 v3, s[0:1], 0, v1, s[0:1]
	s_waitcnt vmcnt(28)
	v_lshlrev_b32_e32 v2, 16, v83
	v_max_f32_e32 v2, v2, v2
	v_med3_f32 v2, v2, s85, v215
	v_mul_f32_e32 v2, 0xbfb8aa3b, v2
	v_exp_f32_e32 v18, v2
	s_mov_b32 s0, 0x11000
	v_add_co_u32_e64 v2, s[0:1], s0, v0
	v_fma_f32 v13, v11, v17, v16
	s_nop 0
	v_addc_co_u32_e64 v3, s[0:1], 0, v1, s[0:1]
	v_mul_f32_e32 v2, v11, v14
	v_mul_f32_e32 v14, v2, v17
	v_add_f32_e32 v2, 1.0, v18
	s_mov_b32 s0, 0x13000
	v_rcp_f32_e32 v19, v2
	v_add_co_u32_e64 v2, s[0:1], s0, v0
	v_fma_f32 v31, v11, v9, v16
	s_nop 0
	v_addc_co_u32_e64 v3, s[0:1], 0, v1, s[0:1]
	s_waitcnt vmcnt(27)
	v_lshlrev_b32_e32 v2, 16, v84
	v_max_f32_e32 v2, v2, v2
	v_med3_f32 v2, v2, s85, v215
	v_mul_f32_e32 v2, 0xbfb8aa3b, v2
	v_exp_f32_e32 v20, v2
	v_mul_f32_e32 v2, v11, v18
	v_mul_f32_e32 v18, v2, v19
	s_mov_b32 s0, 0x15000
	v_add_f32_e32 v2, 1.0, v20
	v_rcp_f32_e32 v21, v2
	s_waitcnt vmcnt(26)
	v_lshlrev_b32_e32 v2, 16, v85
	v_max_f32_e32 v2, v2, v2
	v_med3_f32 v2, v2, s85, v215
	v_mul_f32_e32 v2, 0xbfb8aa3b, v2
	v_exp_f32_e32 v23, v2
	v_add_co_u32_e64 v2, s[0:1], s0, v0
	v_fma_f32 v17, v11, v19, v16
	s_nop 0
	v_addc_co_u32_e64 v3, s[0:1], 0, v1, s[0:1]
	v_add_f32_e32 v3, 1.0, v23
	v_rcp_f32_e32 v30, v3
	s_waitcnt vmcnt(25)
	v_lshlrev_b32_e32 v3, 16, v86
	v_max_f32_e32 v3, v3, v3
	v_med3_f32 v3, v3, s85, v215
	v_mul_f32_e32 v3, 0xbfb8aa3b, v3
	v_exp_f32_e32 v33, v3
	v_mul_f32_e32 v2, v11, v20
	v_fma_f32 v19, v11, v21, v16
	v_mul_f32_e32 v21, v2, v21
	v_add_f32_e32 v2, 1.0, v33
	s_mov_b32 s0, 0x17000
	v_rcp_f32_e32 v34, v2
	v_add_co_u32_e64 v2, s[0:1], s0, v0
	v_mul_f32_e32 v23, v11, v23
	s_nop 0
	v_addc_co_u32_e64 v3, s[0:1], 0, v1, s[0:1]
	s_mov_b32 s0, 0x19000
	v_add_co_u32_e64 v2, s[0:1], s0, v0
	v_fma_f32 v20, v11, v30, v16
	s_nop 0
	v_addc_co_u32_e64 v3, s[0:1], 0, v1, s[0:1]
	s_mov_b32 s0, 0x1b000
	s_nop 0
	v_add_co_u32_e64 v24, s[0:1], s0, v0
	v_fma_f32 v12, v11, v10, v16
	s_nop 0
	v_addc_co_u32_e64 v25, s[0:1], 0, v1, s[0:1]
	s_waitcnt vmcnt(24)
	v_lshlrev_b32_e32 v2, 16, v87
	v_max_f32_e32 v2, v2, v2
	v_med3_f32 v2, v2, s85, v215
	v_mul_f32_e32 v2, 0xbfb8aa3b, v2
	v_exp_f32_e32 v2, v2
	v_mul_f32_e32 v24, v23, v30
	v_mul_f32_e32 v3, v11, v33
	v_mul_f32_e32 v26, v3, v34
	v_add_f32_e32 v25, 1.0, v2
	v_rcp_f32_e32 v30, v25
	s_waitcnt vmcnt(23)
	v_lshlrev_b32_e32 v25, 16, v88
	v_max_f32_e32 v25, v25, v25
	v_med3_f32 v25, v25, s85, v215
	v_mul_f32_e32 v25, 0xbfb8aa3b, v25
	v_exp_f32_e32 v33, v25
	v_fma_f32 v23, v11, v34, v16
	v_mul_f32_e32 v2, v11, v2
	v_fma_f32 v25, v11, v30, v16
	v_add_f32_e32 v3, 1.0, v33
	v_rcp_f32_e32 v34, v3
	s_waitcnt vmcnt(22)
	v_lshlrev_b32_e32 v3, 16, v89
	v_max_f32_e32 v3, v3, v3
	v_med3_f32 v3, v3, s85, v215
	v_mul_f32_e32 v3, 0xbfb8aa3b, v3
	v_exp_f32_e32 v37, v3
	v_mul_f32_e32 v28, v2, v30
	v_mul_f32_e32 v30, v11, v33
	s_mov_b32 s0, 0x1d000
	v_add_f32_e32 v2, 1.0, v37
	v_rcp_f32_e32 v33, v2
	s_waitcnt vmcnt(21)
	v_lshlrev_b32_e32 v2, 16, v90
	v_max_f32_e32 v2, v2, v2
	v_med3_f32 v2, v2, s85, v215
	v_mul_f32_e32 v2, 0xbfb8aa3b, v2
	v_exp_f32_e32 v39, v2
	v_add_co_u32_e64 v2, s[0:1], s0, v0
	v_fma_f32 v27, v11, v34, v16
	s_nop 0
	v_addc_co_u32_e64 v3, s[0:1], 0, v1, s[0:1]
	v_add_f32_e32 v2, 1.0, v39
	s_mov_b32 s0, 0x1f000
	v_mul_f32_e32 v30, v30, v34
	v_mul_f32_e32 v34, v11, v37
	v_rcp_f32_e32 v37, v2
	v_add_co_u32_e64 v2, s[0:1], s0, v0
	v_fma_f32 v29, v11, v33, v16
	s_nop 0
	v_addc_co_u32_e64 v3, s[0:1], 0, v1, s[0:1]
	s_waitcnt vmcnt(20)
	v_lshlrev_b32_e32 v2, 16, v91
	v_max_f32_e32 v2, v2, v2
	v_med3_f32 v2, v2, s85, v215
	v_mul_f32_e32 v2, 0xbfb8aa3b, v2
	s_mov_b32 s0, 0x20000
	v_exp_f32_e32 v40, v2
	v_add_co_u32_e64 v2, s[0:1], s0, v0
	v_mul_f32_e32 v33, v34, v33
	s_nop 0
	v_addc_co_u32_e64 v3, s[0:1], 0, v1, s[0:1]
	v_add_f32_e32 v2, 1.0, v40
	s_mov_b32 s0, 0x22000
	v_mul_f32_e32 v34, v11, v39
	v_rcp_f32_e32 v39, v2
	v_add_co_u32_e64 v2, s[0:1], s0, v0
	v_fma_f32 v32, v11, v37, v16
	s_nop 0
	v_addc_co_u32_e64 v3, s[0:1], 0, v1, s[0:1]
	s_waitcnt vmcnt(19)
	v_lshlrev_b32_e32 v2, 16, v92
	v_max_f32_e32 v2, v2, v2
	v_med3_f32 v2, v2, s85, v215
	v_mul_f32_e32 v2, 0xbfb8aa3b, v2
	v_exp_f32_e32 v41, v2
	s_mov_b32 s0, 0x24000
	v_mul_f32_e32 v35, v34, v37
	v_mul_f32_e32 v37, v11, v40
	v_add_f32_e32 v2, 1.0, v41
	v_rcp_f32_e32 v40, v2
	v_add_co_u32_e64 v2, s[0:1], s0, v0
	v_fma_f32 v34, v11, v39, v16
	s_nop 0
	v_addc_co_u32_e64 v3, s[0:1], 0, v1, s[0:1]
	s_waitcnt vmcnt(18)
	v_lshlrev_b32_e32 v2, 16, v93
	v_max_f32_e32 v2, v2, v2
	v_med3_f32 v2, v2, s85, v215
	v_mul_f32_e32 v2, 0xbfb8aa3b, v2
	v_exp_f32_e32 v45, v2
	s_mov_b32 s0, 0x26000
	v_mul_f32_e32 v37, v37, v39
	v_mul_f32_e32 v39, v11, v41
	v_add_f32_e32 v2, 1.0, v45
	v_rcp_f32_e32 v47, v2
	s_waitcnt vmcnt(17)
	v_lshlrev_b32_e32 v2, 16, v94
	v_max_f32_e32 v2, v2, v2
	v_med3_f32 v2, v2, s85, v215
	v_mul_f32_e32 v2, 0xbfb8aa3b, v2
	v_exp_f32_e32 v49, v2
	v_add_co_u32_e64 v2, s[0:1], s0, v0
	v_fma_f32 v36, v11, v40, v16
	s_nop 0
	v_addc_co_u32_e64 v3, s[0:1], 0, v1, s[0:1]
	v_add_f32_e32 v2, 1.0, v49
	s_mov_b32 s0, 0x28000
	v_rcp_f32_e32 v51, v2
	v_add_co_u32_e64 v2, s[0:1], s0, v0
	v_mul_f32_e32 v39, v39, v40
	s_nop 0
	v_addc_co_u32_e64 v3, s[0:1], 0, v1, s[0:1]
	s_mov_b32 s0, 0x2a000
	s_nop 0
	v_add_co_u32_e64 v40, s[0:1], s0, v0
	v_fma_f32 v38, v11, v47, v16
	s_nop 0
	v_addc_co_u32_e64 v41, s[0:1], 0, v1, s[0:1]
	s_waitcnt vmcnt(16)
	v_lshlrev_b32_e32 v2, 16, v95
	v_max_f32_e32 v2, v2, v2
	v_med3_f32 v2, v2, s85, v215
	v_mul_f32_e32 v2, 0xbfb8aa3b, v2
	v_exp_f32_e32 v2, v2
	s_waitcnt vmcnt(15)
	v_lshlrev_b32_e32 v42, 16, v96
	v_max_f32_e32 v42, v42, v42
	v_med3_f32 v42, v42, s85, v215
	v_mul_f32_e32 v3, v11, v45
	v_mul_f32_e32 v42, 0xbfb8aa3b, v42
	v_mul_f32_e32 v41, v3, v47
	v_add_f32_e32 v3, 1.0, v2
	v_exp_f32_e32 v47, v42
	v_mul_f32_e32 v42, v11, v49
	v_fma_f32 v40, v11, v51, v16
	v_rcp_f32_e32 v3, v3
	v_mul_f32_e32 v43, v42, v51
	s_waitcnt vmcnt(14)
	v_lshlrev_b32_e32 v44, 16, v97
	v_max_f32_e32 v44, v44, v44
	v_med3_f32 v44, v44, s85, v215
	v_mul_f32_e32 v44, 0xbfb8aa3b, v44
	v_exp_f32_e32 v51, v44
	v_add_f32_e32 v45, 1.0, v47
	v_mul_f32_e32 v2, v11, v2
	v_rcp_f32_e32 v49, v45
	v_mul_f32_e32 v45, v2, v3
	v_add_f32_e32 v2, 1.0, v51
	v_rcp_f32_e32 v53, v2
	s_waitcnt vmcnt(13)
	v_lshlrev_b32_e32 v2, 16, v98
	v_max_f32_e32 v2, v2, v2
	v_med3_f32 v2, v2, s85, v215
	v_mul_f32_e32 v2, 0xbfb8aa3b, v2
	v_exp_f32_e32 v54, v2
	s_mov_b32 s0, 0x2c000
	v_add_co_u32_e64 v2, s[0:1], s0, v0
	v_fma_f32 v42, v11, v3, v16
	s_nop 0
	v_addc_co_u32_e64 v3, s[0:1], 0, v1, s[0:1]
	v_mul_f32_e32 v2, v11, v47
	v_mul_f32_e32 v47, v2, v49
	v_add_f32_e32 v2, 1.0, v54
	v_rcp_f32_e32 v55, v2
	s_waitcnt vmcnt(12)
	v_lshlrev_b32_e32 v2, 16, v99
	v_max_f32_e32 v2, v2, v2
	v_med3_f32 v2, v2, s85, v215
	v_mul_f32_e32 v2, 0xbfb8aa3b, v2
	v_exp_f32_e32 v56, v2
	v_mul_f32_e32 v2, v11, v51
	v_fma_f32 v44, v11, v49, v16
	v_mul_f32_e32 v49, v2, v53
	v_add_f32_e32 v2, 1.0, v56
	s_mov_b32 s0, 0x2e000
	v_fma_f32 v46, v11, v53, v16
	v_rcp_f32_e32 v53, v2
	v_add_co_u32_e64 v2, s[0:1], s0, v0
	v_fma_f32 v48, v11, v55, v16
	s_nop 0
	v_addc_co_u32_e64 v3, s[0:1], 0, v1, s[0:1]
	s_mov_b32 s0, 0x30000
	v_add_co_u32_e64 v2, s[0:1], s0, v0
	s_nop 1
	v_addc_co_u32_e64 v3, s[0:1], 0, v1, s[0:1]
	s_waitcnt vmcnt(11)
	v_lshlrev_b32_e32 v2, 16, v100
	v_max_f32_e32 v2, v2, v2
	v_med3_f32 v2, v2, s85, v215
	v_mul_f32_e32 v2, 0xbfb8aa3b, v2
	v_exp_f32_e32 v59, v2
	v_mul_f32_e32 v2, v11, v54
	v_mul_f32_e32 v51, v2, v55
	s_mov_b32 s0, 0x32000
	v_add_f32_e32 v2, 1.0, v59
	v_rcp_f32_e32 v55, v2
	v_add_co_u32_e64 v2, s[0:1], s0, v0
	v_fma_f32 v50, v11, v53, v16
	s_nop 0
	v_addc_co_u32_e64 v3, s[0:1], 0, v1, s[0:1]
	s_mov_b32 s0, 0x34000
	v_add_co_u32_e64 v2, s[0:1], s0, v0
	s_nop 1
	v_addc_co_u32_e64 v3, s[0:1], 0, v1, s[0:1]
	s_waitcnt vmcnt(10)
	v_lshlrev_b32_e32 v2, 16, v101
	v_max_f32_e32 v2, v2, v2
	v_med3_f32 v2, v2, s85, v215
	v_mul_f32_e32 v2, 0xbfb8aa3b, v2
	v_exp_f32_e32 v52, v2
	v_mul_f32_e32 v2, v11, v56
	v_mul_f32_e32 v54, v2, v53
	s_mov_b32 s0, 0x36000
	v_add_f32_e32 v2, 1.0, v52
	v_rcp_f32_e32 v60, v2
	v_add_co_u32_e64 v2, s[0:1], s0, v0
	v_mul_f32_e32 v52, v11, v52
	s_nop 0
	v_addc_co_u32_e64 v3, s[0:1], 0, v1, s[0:1]
	s_mov_b32 s0, 0x38000
	v_add_co_u32_e64 v2, s[0:1], s0, v0
	v_fma_f32 v53, v11, v55, v16
	s_nop 0
	v_addc_co_u32_e64 v3, s[0:1], 0, v1, s[0:1]
	v_mul_f32_e32 v2, v11, v59
	v_mul_f32_e32 v56, v2, v55
	s_waitcnt vmcnt(9)
	v_lshlrev_b32_e32 v2, 16, v102
	v_max_f32_e32 v2, v2, v2
	v_med3_f32 v2, v2, s85, v215
	v_mul_f32_e32 v2, 0xbfb8aa3b, v2
	s_mov_b32 s0, 0x3a000
	v_exp_f32_e32 v59, v2
	v_add_co_u32_e64 v2, s[0:1], s0, v0
	v_fma_f32 v55, v11, v60, v16
	s_nop 0
	v_addc_co_u32_e64 v3, s[0:1], 0, v1, s[0:1]
	s_mov_b32 s0, 0x3c000
	s_nop 0
	v_add_co_u32_e64 v0, s[0:1], s0, v0
	s_nop 0
	v_addc_co_u32_e64 v1, s[0:1], 0, v1, s[0:1]
	s_waitcnt vmcnt(8)
	v_lshlrev_b32_e32 v3, 16, v103
	v_max_f32_e32 v1, v3, v3
	v_med3_f32 v1, v1, s85, v215
	v_add_f32_e32 v3, 1.0, v59
	v_mul_f32_e32 v1, 0xbfb8aa3b, v1
	v_rcp_f32_e32 v3, v3
	v_exp_f32_e32 v1, v1
	v_mul_f32_e32 v59, v11, v59
	v_mul_f32_e32 v58, v52, v60
	v_fma_f32 v57, v11, v3, v16
	v_mul_f32_e32 v60, v59, v3
	s_waitcnt vmcnt(7)
	v_lshlrev_b32_e32 v3, 16, v104
	v_add_f32_e32 v52, 1.0, v1
	v_max_f32_e32 v3, v3, v3
	s_waitcnt vmcnt(6)
	v_lshlrev_b32_e32 v61, 16, v105
	v_rcp_f32_e32 v52, v52
	v_med3_f32 v3, v3, s85, v215
	v_max_f32_e32 v61, v61, v61
	v_mul_f32_e32 v3, 0xbfb8aa3b, v3
	v_med3_f32 v61, v61, s85, v215
	v_exp_f32_e32 v3, v3
	v_mul_f32_e32 v61, 0xbfb8aa3b, v61
	v_mul_f32_e32 v1, v11, v1
	v_exp_f32_e32 v67, v61
	v_fma_f32 v59, v11, v52, v16
	v_mul_f32_e32 v62, v1, v52
	v_add_f32_e32 v61, 1.0, v3
	v_rcp_f32_e32 v63, v61
	v_add_f32_e32 v1, 1.0, v67
	v_rcp_f32_e32 v1, v1
	s_waitcnt vmcnt(5)
	v_lshlrev_b32_e32 v52, 16, v106
	v_max_f32_e32 v52, v52, v52
	v_med3_f32 v52, v52, s85, v215
	v_mul_f32_e32 v52, 0xbfb8aa3b, v52
	v_exp_f32_e32 v52, v52
	v_mul_f32_e32 v3, v11, v3
	s_waitcnt vmcnt(4)
	v_lshlrev_b32_e32 v65, 16, v107
	v_max_f32_e32 v65, v65, v65
	v_med3_f32 v65, v65, s85, v215
	v_mul_f32_e32 v64, v3, v63
	v_mul_f32_e32 v3, v11, v67
	v_mul_f32_e32 v65, 0xbfb8aa3b, v65
	v_exp_f32_e32 v71, v65
	v_add_f32_e32 v65, 1.0, v52
	v_mul_f32_e32 v66, v3, v1
	v_mul_f32_e32 v3, v11, v52
	v_fma_f32 v61, v11, v63, v16
	v_fma_f32 v63, v11, v1, v16
	v_rcp_f32_e32 v67, v65
	v_add_f32_e32 v1, 1.0, v71
	v_rcp_f32_e32 v1, v1
	v_cmp_gt_i32_e64 s[0:1], 3, v15
	v_mul_f32_e32 v68, v3, v67
	s_waitcnt vmcnt(3)
	v_lshlrev_b32_e32 v52, 16, v108
	v_max_f32_e32 v52, v52, v52
	v_med3_f32 v52, v52, s85, v215
	v_mul_f32_e32 v52, 0xbfb8aa3b, v52
	v_exp_f32_e32 v52, v52
	v_mul_f32_e32 v3, v11, v71
	s_waitcnt vmcnt(2)
	v_lshlrev_b32_e32 v69, 16, v109
	v_max_f32_e32 v69, v69, v69
	v_med3_f32 v69, v69, s85, v215
	v_mul_f32_e32 v69, 0xbfb8aa3b, v69
	v_exp_f32_e32 v73, v69
	v_add_f32_e32 v69, 1.0, v52
	v_fma_f32 v65, v11, v67, v16
	v_fma_f32 v67, v11, v1, v16
	v_rcp_f32_e32 v71, v69
	v_mul_f32_e32 v70, v3, v1
	v_add_f32_e32 v1, 1.0, v73
	v_rcp_f32_e32 v1, v1
	v_mul_f32_e32 v3, v11, v52
	v_mul_f32_e32 v72, v3, v71
	v_mul_f32_e32 v3, v11, v73
	v_fma_f32 v69, v11, v71, v16
	v_fma_f32 v71, v11, v1, v16
	v_mul_f32_e32 v74, v3, v1
	s_waitcnt vmcnt(1)
	v_lshlrev_b32_e32 v2, 16, v110
	v_max_f32_e32 v2, v2, v2
	s_waitcnt vmcnt(0)
	v_lshlrev_b32_e32 v0, 16, v111
	v_max_f32_e32 v0, v0, v0
	v_med3_f32 v0, v0, s85, v215
	v_mul_f32_e32 v0, 0xbfb8aa3b, v0
	v_exp_f32_e32 v0, v0
	v_med3_f32 v2, v2, s85, v215
	v_mul_f32_e32 v2, 0xbfb8aa3b, v2
	v_exp_f32_e32 v2, v2
	v_add_f32_e32 v1, 1.0, v0
	v_rcp_f32_e32 v1, v1
	v_mul_f32_e32 v0, v11, v0
	v_add_f32_e32 v52, 1.0, v2
	v_rcp_f32_e32 v52, v52
	v_mul_f32_e32 v78, v0, v1
	v_mul_f32_e32 v0, v31, v12
	v_mul_f32_e32 v0, v0, v13
	v_mul_f32_e32 v0, v0, v17
	v_mul_f32_e32 v0, v0, v19
	v_mul_f32_e32 v0, v0, v20
	v_mul_f32_e32 v0, v0, v23
	v_mul_f32_e32 v0, v0, v25
	v_mul_f32_e32 v0, v0, v27
	v_mul_f32_e32 v0, v0, v29
	v_mul_f32_e32 v0, v0, v32
	v_mul_f32_e32 v0, v0, v34
	v_mul_f32_e32 v0, v0, v36
	v_mul_f32_e32 v0, v0, v38
	v_mul_f32_e32 v0, v0, v40
	v_mul_f32_e32 v0, v0, v42
	v_mul_f32_e32 v0, v0, v44
	v_mul_f32_e32 v0, v0, v46
	v_mul_f32_e32 v0, v0, v48
	v_mul_f32_e32 v0, v0, v50
	v_mul_f32_e32 v0, v0, v53
	v_mul_f32_e32 v0, v0, v55
	v_mul_f32_e32 v0, v0, v57
	v_mul_f32_e32 v0, v0, v59
	v_mul_f32_e32 v0, v0, v61
	v_mul_f32_e32 v0, v0, v63
	v_mul_f32_e32 v0, v0, v65
	v_mul_f32_e32 v0, v0, v67
	v_mul_f32_e32 v0, v0, v69
	v_fma_f32 v73, v11, v52, v16
	v_mul_f32_e32 v0, v0, v71
	v_mul_f32_e32 v2, v11, v2
	v_fmac_f32_e32 v16, v11, v1
	v_mul_f32_e32 v0, v0, v73
	v_mul_f32_e32 v76, v2, v52
	v_mul_f32_e32 v52, v0, v16
	v_lshl_add_u32 v0, v5, 2, v75
	v_lshl_add_u32 v1, v15, 8, v0
	ds_write_b32 v1, v52 offset:55296
	s_waitcnt lgkmcnt(0)
	s_barrier
	ds_read2st64_b32 v[2:3], v0 offset0:216 offset1:217
	ds_read2st64_b32 v[0:1], v0 offset0:218 offset1:219
	v_mul_lo_u32 v75, v15, s2
	v_add3_u32 v22, v22, v75, v128
	s_and_saveexec_b64 s[2:3], vcc
	s_xor_b64 s[2:3], exec, s[2:3]
	s_cbranch_execz .LBB0_312
	v_cmp_lt_i32_e32 vcc, 0, v15
	s_waitcnt lgkmcnt(1)
	s_nop 0
	v_cndmask_b32_e32 v16, 1.0, v2, vcc
	v_mul_f32_e32 v75, v16, v3
	v_cmp_lt_i32_e32 vcc, 1, v15
	s_nop 1
	v_cndmask_b32_e32 v16, v16, v75, vcc
	s_waitcnt lgkmcnt(0)
	v_mul_f32_e32 v75, v0, v16
	v_cmp_lt_i32_e32 vcc, 2, v15
	s_nop 1
	v_cndmask_b32_e32 v16, v16, v75, vcc
	v_mul_f32_e32 v75, v1, v16
	v_cmp_lt_i32_e32 vcc, 3, v15
	s_nop 1
	v_cndmask_b32_e32 v75, v16, v75, vcc
	v_mul_f32_e32 v77, v31, v75
	v_mul_f32_e32 v12, v12, v77
	v_mul_f32_e32 v14, v14, v12
	v_mul_f32_e32 v12, v13, v12
	v_mul_f32_e32 v13, v18, v12
	v_cvt_pk_bf16_f32 v13, v13, s0
	v_mul_f32_e32 v12, v17, v12
	ds_write_b16 v22, v13 offset:432
	v_mul_f32_e32 v13, v21, v12
	v_cvt_pk_bf16_f32 v13, v13, s0
	v_mul_f32_e32 v12, v19, v12
	ds_write_b16 v22, v13 offset:576
	v_mul_f32_e32 v13, v24, v12
	v_cvt_pk_bf16_f32 v13, v13, s0
	v_mul_f32_e32 v12, v20, v12
	ds_write_b16 v22, v13 offset:720
	v_mul_f32_e32 v13, v26, v12
	v_cvt_pk_bf16_f32 v13, v13, s0
	v_mul_f32_e32 v12, v23, v12
	ds_write_b16 v22, v13 offset:864
	v_mul_f32_e32 v13, v28, v12
	v_cvt_pk_bf16_f32 v13, v13, s0
	v_mul_f32_e32 v12, v25, v12
	ds_write_b16 v22, v13 offset:1008
	v_mul_f32_e32 v13, v30, v12
	v_cvt_pk_bf16_f32 v13, v13, s0
	v_mul_f32_e32 v12, v27, v12
	ds_write_b16 v22, v13 offset:1152
	v_mul_f32_e32 v13, v33, v12
	v_cvt_pk_bf16_f32 v13, v13, s0
	v_mul_f32_e32 v12, v29, v12
	ds_write_b16 v22, v13 offset:1296
	v_mul_f32_e32 v13, v35, v12
	v_cvt_pk_bf16_f32 v13, v13, s0
	v_mul_f32_e32 v12, v32, v12
	ds_write_b16 v22, v13 offset:1440
	v_mul_f32_e32 v13, v37, v12
	v_cvt_pk_bf16_f32 v13, v13, s0
	v_mul_f32_e32 v12, v34, v12
	ds_write_b16 v22, v13 offset:1584
	v_mul_f32_e32 v13, v39, v12
	v_cvt_pk_bf16_f32 v13, v13, s0
	v_mul_f32_e32 v12, v36, v12
	ds_write_b16 v22, v13 offset:1728
	v_mul_f32_e32 v13, v41, v12
	v_cvt_pk_bf16_f32 v13, v13, s0
	v_mul_f32_e32 v12, v38, v12
	ds_write_b16 v22, v13 offset:1872
	v_mul_f32_e32 v13, v43, v12
	v_cvt_pk_bf16_f32 v13, v13, s0
	v_mul_f32_e32 v12, v40, v12
	ds_write_b16 v22, v13 offset:2016
	v_mul_f32_e32 v13, v45, v12
	v_cvt_pk_bf16_f32 v13, v13, s0
	v_mul_f32_e32 v12, v42, v12
	ds_write_b16 v22, v13 offset:2160
	v_mul_f32_e32 v13, v47, v12
	v_cvt_pk_bf16_f32 v13, v13, s0
	v_mul_f32_e32 v12, v44, v12
	ds_write_b16 v22, v13 offset:2304
	v_mul_f32_e32 v13, v49, v12
	v_cvt_pk_bf16_f32 v13, v13, s0
	v_mul_f32_e32 v12, v46, v12
	ds_write_b16 v22, v13 offset:2448
	v_mul_f32_e32 v13, v51, v12
	v_cvt_pk_bf16_f32 v13, v13, s0
	v_mul_f32_e32 v12, v48, v12
	ds_write_b16 v22, v13 offset:2592
	v_mul_f32_e32 v13, v54, v12
	v_cvt_pk_bf16_f32 v13, v13, s0
	v_mul_f32_e32 v12, v50, v12
	ds_write_b16 v22, v13 offset:2736
	v_mul_f32_e32 v13, v56, v12
	v_cvt_pk_bf16_f32 v13, v13, s0
	v_mul_f32_e32 v12, v53, v12
	ds_write_b16 v22, v13 offset:2880
	v_mul_f32_e32 v13, v58, v12
	v_cvt_pk_bf16_f32 v13, v13, s0
	v_mul_f32_e32 v12, v55, v12
	ds_write_b16 v22, v13 offset:3024
	v_mul_f32_e32 v13, v60, v12
	v_cvt_pk_bf16_f32 v13, v13, s0
	v_mul_f32_e32 v12, v57, v12
	ds_write_b16 v22, v13 offset:3168
	v_mul_f32_e32 v13, v62, v12
	v_cvt_pk_bf16_f32 v13, v13, s0
	v_mul_f32_e32 v12, v59, v12
	ds_write_b16 v22, v13 offset:3312
	v_mul_f32_e32 v13, v64, v12
	v_cvt_pk_bf16_f32 v13, v13, s0
	v_mul_f32_e32 v12, v61, v12
	ds_write_b16 v22, v13 offset:3456
	v_mul_f32_e32 v13, v66, v12
	v_cvt_pk_bf16_f32 v13, v13, s0
	v_mul_f32_e32 v12, v63, v12
	ds_write_b16 v22, v13 offset:3600
	v_mul_f32_e32 v13, v68, v12
	v_cvt_pk_bf16_f32 v13, v13, s0
	v_mul_f32_e32 v12, v65, v12
	ds_write_b16 v22, v13 offset:3744
	v_mul_f32_e32 v13, v70, v12
	v_cvt_pk_bf16_f32 v13, v13, s0
	v_mul_f32_e32 v12, v67, v12
	ds_write_b16 v22, v13 offset:3888
	v_mul_f32_e32 v13, v72, v12
	v_cvt_pk_bf16_f32 v13, v13, s0
	v_mul_f32_e32 v12, v69, v12
	ds_write_b16 v22, v13 offset:4032
	v_mul_f32_e32 v13, v74, v12
	v_cvt_pk_bf16_f32 v13, v13, s0
	v_mul_f32_e32 v12, v71, v12
	ds_write_b16 v22, v13 offset:4176
	v_mul_f32_e32 v13, v76, v12
	v_mul_f32_e32 v12, v73, v12
	v_mul_f32_e32 v12, v78, v12
	v_cvt_pk_bf16_f32 v14, v14, s0
	v_cvt_pk_bf16_f32 v13, v13, s0
	v_cvt_pk_bf16_f32 v12, v12, s0
	ds_write_b16 v22, v14 offset:288
	ds_write_b16 v22, v13 offset:4320
	ds_write_b16 v22, v12 offset:4464
